# v043 with in-proj GEMM start-stagger unit 0x78 instead of 0x64
# speedup vs baseline: 1.0072x; 1.0072x over previous
.LBB0_119:
	s_add_i32 s0, s0, -1
	s_cmp_lg_u32 s0, 0
	s_sleep 0x78
	s_cbranch_scc1 .LBB0_119
